# FoX: static s_setprio 1 for waves 4-7 removed (all waves equal priority) with the pipelined loop
# speedup vs baseline: 1.0100x; 1.0061x over previous
.LBB0_172:
	s_and_b32 s38, s43, 6
	s_xor_b32 s38, s38, 15
	s_and_b32 s37, s43, 1
	s_sub_i32 s38, s38, s42
	s_or_b32 s39, s43, s42
	s_cmp_eq_u32 s37, 0
	s_cselect_b32 s38, s39, s38
	s_lshl_b32 s44, s38, 8
	v_add_u32_e32 v182, s44, v205
	v_ashrrev_i32_e32 v183, 31, v182
	v_and_b32_e32 v2, 0xfe0, v182
	v_mov_b32_e32 v3, v0
	v_lshlrev_b64 v[2:3], 7, v[2:3]
	v_lshl_add_u64 v[2:3], v[176:177], 0, v[2:3]
	global_load_dwordx4 v[66:69], v[2:3], off
	global_load_dwordx4 v[70:73], v[2:3], off offset:1024
	global_load_dwordx4 v[74:77], v[2:3], off offset:2048
	global_load_dwordx4 v[78:81], v[2:3], off offset:3072
	v_mov_b32_e32 v1, 0x3f80
	v_cndmask_b32_e64 v196, 0, v1, s[16:17]
	v_mov_b32_e32 v197, v0
	v_mov_b32_e32 v198, v0
	v_mov_b32_e32 v199, v0
	v_mov_b32_e32 v162, v0
	v_mov_b32_e32 v163, v0
	v_mov_b32_e32 v164, v0
	v_mov_b32_e32 v165, v0
	s_andn2_b64 vcc, exec, s[30:31]
	s_cbranch_vccnz .LBB0_174
	s_nop 0
